# v3 + layer-0 seam after phase B uses the XCD barrier instead of cg grid sync
# speedup vs baseline: 1.0102x; 1.0080x over previous
.LBB0_391:
	v_readlane_b32 s0, v255, 14
	v_readlane_b32 s1, v255, 15
	s_mov_b64 s[6:7], -1
	s_mov_b64 s[0:1], s[74:75]
	s_load_dwordx2 s[8:9], s[0:1], 0xa8
	v_readlane_b32 s0, v255, 12
	v_readlane_b32 s1, v255, 13
	s_mov_b64 s[12:13], 0
	s_and_b64 vcc, exec, s[0:1]
	s_getreg_b32 s0, hwreg(HW_REG_XCC_ID, 0, 4)
	s_cbranch_vccnz .LBB0_394
	v_mov_b32_e32 v0, v1
	s_nop 0
	v_mbcnt_lo_u32_b32 v0, -1, v0
	v_mbcnt_hi_u32_b32 v0, -1, v0
	v_cmp_eq_u32_e32 vcc, 0, v0
	s_and_b64 s[12:13], vcc, exec

.LBB0_447:
.LBB0_459:
	s_mov_b64 s[0:1], s[74:75]
	s_load_dwordx2 s[6:7], s[0:1], 0xa8
	v_mov_b32_e32 v0, v1
	s_waitcnt lgkmcnt(0)
	v_readlane_b32 s0, v254, 10
	v_mbcnt_lo_u32_b32 v0, -1, v0
	v_mbcnt_hi_u32_b32 v0, -1, v0
	v_readlane_b32 s1, v254, 11
	v_add_u32_e32 v6, s54, v0
	s_andn2_b64 vcc, exec, s[0:1]
	v_cndmask_b32_e64 v0, 0, 1, s[0:1]
	v_cmp_ne_u32_e64 s[12:13], 1, v0
	s_cbranch_vccnz .LBB0_472
	v_max_i32_e32 v2, 0x1e00, v6
	v_sub_u32_e32 v2, v2, v6
	v_add_u32_e32 v2, 0x1ff, v2
	v_lshrrev_b32_e32 v3, 9, v2
	v_and_b32_e32 v0, 0x7f, v6
	v_add_u32_e32 v3, 1, v3
	v_and_b32_e32 v4, 0x600, v2
	s_movk_i32 s8, 0x600
	s_add_u32 s0, s6, 0x21f00000
	v_lshl_add_u32 v7, v0, 2, 0
	v_and_b32_e32 v3, 3, v3
	v_cmp_ne_u32_e64 s[14:15], s8, v4
	s_movk_i32 s8, 0x5ff
	v_lshlrev_b32_e32 v0, 1, v0
	s_addc_u32 s1, s7, 0
	v_cmp_lt_u32_e64 s[16:17], s8, v2
	v_sub_u32_e32 v9, 0, v3
	v_lshl_add_u64 v[2:3], s[6:7], 0, v[0:1]
	s_mov_b64 s[6:7], 0x19f00700
	v_cmp_gt_i32_e32 vcc, s37, v6
	v_lshlrev_b32_e32 v8, 2, v6
	v_lshl_add_u64 v[2:3], v[2:3], 0, s[6:7]
	v_readlane_b32 s26, v254, 9
